# MFMA-first reorder removed (latent race), parked-O touch removed; gate + next-Q touches, unit order 31-s,s,16+s,15-s, rest as v93
# speedup vs baseline: 1.0328x; 1.0289x over previous
.LBB0_647:
	s_mov_b32 s25, s24
	s_mov_b32 s1, s2
	v_lshl_add_u32 v214, s27, 1, v248
	ds_read_b64_tr_b16 v[66:67], v214 offset:24576
	ds_read_b64_tr_b16 v[68:69], v214 offset:25088
	v_add_f32_e32 v65, v96, v97
	v_add_f32_e32 v65, v98, v65
	v_add_f32_e32 v65, v99, v65
	v_add_f32_e32 v65, v100, v65
	v_add_f32_e32 v65, v101, v65
	v_cvt_pk_bf16_f32 v160, v96, v97
	v_cvt_pk_bf16_f32 v161, v98, v99
	s_waitcnt lgkmcnt(9)
	v_mfma_f32_32x32x16_bf16 v[128:143], v[204:207], v[172:175], 0
	ds_read_b64_tr_b16 v[70:71], v214 offset:28672
	ds_read_b64_tr_b16 v[72:73], v214 offset:29184
	v_add_f32_e32 v65, v102, v65
	v_add_f32_e32 v65, v103, v65
	v_add_f32_e32 v65, v104, v65
	v_add_f32_e32 v65, v105, v65
	v_cvt_pk_bf16_f32 v162, v100, v101
	v_cvt_pk_bf16_f32 v163, v102, v103
	s_waitcnt lgkmcnt(10)
	v_mfma_f32_32x32x16_bf16 v[112:127], v[200:203], v[172:175], 0
	ds_read_b64_tr_b16 v[74:75], v214 offset:25600
	ds_read_b64_tr_b16 v[76:77], v214 offset:26112
	v_add_f32_e32 v65, v106, v65
	v_add_f32_e32 v65, v107, v65
	v_add_f32_e32 v65, v108, v65
	v_add_f32_e32 v65, v109, v65
	v_cvt_pk_bf16_f32 v152, v104, v105
	v_cvt_pk_bf16_f32 v153, v106, v107
	s_waitcnt lgkmcnt(11)
	v_mfma_f32_32x32x16_bf16 v[128:143], v[196:199], v[168:171], v[128:143]
	ds_read_b64_tr_b16 v[96:97], v214 offset:29696
	ds_read_b64_tr_b16 v[98:99], v214 offset:30208
	v_add_f32_e32 v65, v110, v65
	v_add_f32_e32 v65, v111, v65
	v_add_f32_e32 v65, v80, v65
	v_add_f32_e32 v65, v81, v65
	v_cvt_pk_bf16_f32 v154, v108, v109
	v_cvt_pk_bf16_f32 v155, v110, v111
	s_waitcnt lgkmcnt(12)
	v_mfma_f32_32x32x16_bf16 v[112:127], v[192:195], v[168:171], v[112:127]
	ds_read_b64_tr_b16 v[100:101], v214 offset:26624
	ds_read_b64_tr_b16 v[102:103], v214 offset:27136
	v_add_f32_e32 v65, v82, v65
	v_add_f32_e32 v65, v83, v65
	v_add_f32_e32 v65, v84, v65
	v_add_f32_e32 v65, v85, v65
	v_cvt_pk_bf16_f32 v148, v80, v81
	v_cvt_pk_bf16_f32 v149, v82, v83
	s_waitcnt lgkmcnt(13)
	v_mfma_f32_32x32x16_bf16 v[128:143], v[188:191], v[164:167], v[128:143]
	ds_read_b64_tr_b16 v[104:105], v214 offset:30720
	ds_read_b64_tr_b16 v[106:107], v214 offset:31232
	v_add_f32_e32 v65, v86, v65
	v_add_f32_e32 v65, v87, v65
	v_add_f32_e32 v65, v88, v65
	v_add_f32_e32 v65, v89, v65
	v_cvt_pk_bf16_f32 v150, v84, v85
	v_cvt_pk_bf16_f32 v151, v86, v87
	s_waitcnt lgkmcnt(14)
	v_mfma_f32_32x32x16_bf16 v[112:127], v[184:187], v[164:167], v[112:127]
	ds_read_b64_tr_b16 v[108:109], v214 offset:27648
	ds_read_b64_tr_b16 v[110:111], v214 offset:28160
	v_add_f32_e32 v65, v90, v65
	v_add_f32_e32 v65, v91, v65
	v_add_f32_e32 v65, v92, v65
	v_add_f32_e32 v65, v93, v65
	v_cvt_pk_bf16_f32 v144, v88, v89
	v_cvt_pk_bf16_f32 v145, v90, v91
	s_waitcnt lgkmcnt(14)
	v_mfma_f32_32x32x16_bf16 v[128:143], v[180:183], v[156:159], v[128:143]
	ds_read_b64_tr_b16 v[86:87], v214 offset:31744
	ds_read_b64_tr_b16 v[88:89], v214 offset:32256
	v_add_f32_e32 v65, v94, v65
	v_add_f32_e32 v65, v95, v65
	v_add_f32_e32 v65, 0, v65
	v_cvt_pk_bf16_f32 v146, v92, v93
	v_cvt_pk_bf16_f32 v147, v94, v95
	v_mfma_f32_32x32x16_bf16 v[112:127], v[176:179], v[156:159], v[112:127]
	s_add_i32 s2, s2, s69
	v_lshl_add_u64 v[78:79], v[212:213], 0, s[16:17]
	s_mov_b32 s24, m0
	s_mov_b32 m0, s2
	s_nop 0
	global_load_lds_dwordx4 v[78:79], off
	s_mov_b32 m0, s24
	s_lshl_b32 s2, s25, 1
	v_lshl_add_u64 v[78:79], v[210:211], 0, s[16:17]
	s_add_i32 s24, s2, s72
	s_mov_b32 s27, m0
	s_mov_b32 m0, s24
	s_nop 0
	global_load_lds_dwordx4 v[78:79], off
	s_mov_b32 m0, s27
	v_lshl_add_u64 v[78:79], v[208:209], 0, s[16:17]
	s_add_i32 s2, s2, s73
	s_mov_b32 s24, m0
	s_mov_b32 m0, s2
	s_nop 0
	global_load_lds_dwordx4 v[78:79], off
	s_mov_b32 m0, s24
	s_waitcnt lgkmcnt(14)
	v_mfma_f32_32x32x16_bf16 v[16:31], v[160:163], v[66:69], v[16:31]
	ds_read_b64_tr_b16 v[90:91], v214 offset:32768
	ds_read_b64_tr_b16 v[92:93], v214 offset:33280
	v_exp_f32_e32 v128, v128
	v_exp_f32_e32 v129, v129
	s_waitcnt lgkmcnt(14)
	v_mfma_f32_32x32x16_bf16 v[48:63], v[160:163], v[70:73], v[48:63]
	ds_read_b64_tr_b16 v[188:189], v214 offset:36864
	ds_read_b64_tr_b16 v[190:191], v214 offset:37376
	v_exp_f32_e32 v130, v130
	v_exp_f32_e32 v131, v131
	v_add_u32_e32 v66, s25, v246
	ds_read_b128 v[82:85], v66
	ds_read_b128 v[78:81], v66 offset:512
	s_waitcnt lgkmcnt(14)
	v_mfma_f32_32x32x16_bf16 v[16:31], v[152:155], v[74:77], v[16:31]
	ds_read_b64_tr_b16 v[192:193], v214 offset:33792
	ds_read_b64_tr_b16 v[194:195], v214 offset:34304
	v_exp_f32_e32 v132, v132
	v_exp_f32_e32 v133, v133
	ds_read_b128 v[184:187], v66 offset:2048
	ds_read_b128 v[176:179], v66 offset:2560
	v_mfma_f32_32x32x16_bf16 v[48:63], v[152:155], v[96:99], v[48:63]
	ds_read_b64_tr_b16 v[196:197], v214 offset:37888
	ds_read_b64_tr_b16 v[198:199], v214 offset:38400
	v_exp_f32_e32 v134, v134
	v_exp_f32_e32 v135, v135
	ds_read_b128 v[180:183], v66 offset:4096
	ds_read_b128 v[70:73], v66 offset:4608
	s_waitcnt lgkmcnt(14)
	v_mfma_f32_32x32x16_bf16 v[16:31], v[148:151], v[100:103], v[16:31]
	ds_read_b64_tr_b16 v[94:95], v214 offset:34816
	ds_read_b64_tr_b16 v[96:97], v214 offset:35328
	v_exp_f32_e32 v136, v136
	v_exp_f32_e32 v137, v137
	ds_read_b128 v[74:77], v66 offset:6144
	ds_read_b128 v[66:69], v66 offset:6656
	v_mfma_f32_32x32x16_bf16 v[48:63], v[148:151], v[104:107], v[48:63]
	ds_read_b64_tr_b16 v[98:99], v214 offset:38912
	ds_read_b64_tr_b16 v[100:101], v214 offset:39424
	v_exp_f32_e32 v138, v138
	v_exp_f32_e32 v139, v139
	v_mfma_f32_32x32x16_bf16 v[16:31], v[144:147], v[108:111], v[16:31]
	ds_read_b64_tr_b16 v[102:103], v214 offset:35840
	ds_read_b64_tr_b16 v[104:105], v214 offset:36352
	v_exp_f32_e32 v140, v140
	v_exp_f32_e32 v141, v141
	v_mfma_f32_32x32x16_bf16 v[48:63], v[144:147], v[86:89], v[48:63]
	ds_read_b64_tr_b16 v[106:107], v214 offset:39936
	ds_read_b64_tr_b16 v[108:109], v214 offset:40448
	v_exp_f32_e32 v142, v142
	v_exp_f32_e32 v143, v143
	s_waitcnt lgkmcnt(14)
	v_mfma_f32_32x32x16_bf16 v[0:15], v[160:163], v[90:93], v[0:15]
	v_exp_f32_e32 v112, v112
	v_exp_f32_e32 v113, v113
	v_mfma_f32_32x32x16_bf16 v[32:47], v[160:163], v[188:191], v[32:47]
	v_exp_f32_e32 v114, v114
	v_exp_f32_e32 v115, v115
	v_mfma_f32_32x32x16_bf16 v[0:15], v[152:155], v[192:195], v[0:15]
	v_exp_f32_e32 v116, v116
	v_exp_f32_e32 v117, v117
	s_waitcnt lgkmcnt(12)
	v_mfma_f32_32x32x16_bf16 v[32:47], v[152:155], v[196:199], v[32:47]
	v_exp_f32_e32 v118, v118
	v_exp_f32_e32 v119, v119
	s_waitcnt lgkmcnt(8)
	v_mfma_f32_32x32x16_bf16 v[0:15], v[148:151], v[94:97], v[0:15]
	v_exp_f32_e32 v120, v120
	v_exp_f32_e32 v121, v121
	s_waitcnt lgkmcnt(4)
	v_mfma_f32_32x32x16_bf16 v[32:47], v[148:151], v[98:101], v[32:47]
	v_exp_f32_e32 v122, v122
	v_exp_f32_e32 v123, v123
	s_waitcnt lgkmcnt(2)
	v_mfma_f32_32x32x16_bf16 v[0:15], v[144:147], v[102:105], v[0:15]
	v_exp_f32_e32 v124, v124
	v_exp_f32_e32 v125, v125
	s_waitcnt lgkmcnt(0)
	v_mfma_f32_32x32x16_bf16 v[32:47], v[144:147], v[106:109], v[32:47]
	v_exp_f32_e32 v126, v126
	v_exp_f32_e32 v127, v127
	s_add_i32 s2, s25, 0x2000
	s_cmpk_lg_i32 s25, 0x4000
	s_cselect_b32 s2, s2, 0
	s_waitcnt vmcnt(3) lgkmcnt(0)
	s_barrier
	v_lshl_add_u32 v214, s1, 1, v248
	ds_read_b64_tr_b16 v[188:189], v214 offset:24576
	ds_read_b64_tr_b16 v[190:191], v214 offset:25088
	v_mfma_f32_32x32x16_bf16 v[96:111], v[82:85], v[172:175], 0
	v_add_f32_e32 v86, v128, v129
	v_add_f32_e32 v86, v130, v86
	v_add_f32_e32 v86, v131, v86
	v_add_f32_e32 v86, v132, v86
	v_add_f32_e32 v86, v133, v86
	v_cvt_pk_bf16_f32 v160, v128, v129
	v_cvt_pk_bf16_f32 v161, v130, v131
	ds_read_b64_tr_b16 v[128:129], v214 offset:28672
	ds_read_b64_tr_b16 v[130:131], v214 offset:29184
	v_add_f32_e32 v82, v134, v86
	v_add_f32_e32 v82, v135, v82
	v_add_f32_e32 v82, v136, v82
	v_add_f32_e32 v144, v137, v82
	v_mfma_f32_32x32x16_bf16 v[80:95], v[78:81], v[172:175], 0
	v_cvt_pk_bf16_f32 v162, v132, v133
	v_cvt_pk_bf16_f32 v163, v134, v135
	ds_read_b64_tr_b16 v[132:133], v214 offset:25600
	ds_read_b64_tr_b16 v[134:135], v214 offset:26112
	v_mfma_f32_32x32x16_bf16 v[96:111], v[184:187], v[168:171], v[96:111]
	v_add_f32_e32 v78, v138, v144
	v_add_f32_e32 v78, v139, v78
	v_add_f32_e32 v78, v140, v78
	v_add_f32_e32 v78, v141, v78
	v_cvt_pk_bf16_f32 v152, v136, v137
	v_cvt_pk_bf16_f32 v153, v138, v139
	ds_read_b64_tr_b16 v[136:137], v214 offset:29696
	ds_read_b64_tr_b16 v[138:139], v214 offset:30208
	v_mfma_f32_32x32x16_bf16 v[80:95], v[176:179], v[168:171], v[80:95]
	v_add_f32_e32 v78, v142, v78
	v_add_f32_e32 v78, v143, v78
	v_add_f32_e32 v78, v112, v78
	v_add_f32_e32 v78, v113, v78
	v_cvt_pk_bf16_f32 v154, v140, v141
	v_cvt_pk_bf16_f32 v155, v142, v143
	ds_read_b64_tr_b16 v[140:141], v214 offset:26624
	ds_read_b64_tr_b16 v[142:143], v214 offset:27136
	v_mfma_f32_32x32x16_bf16 v[96:111], v[180:183], v[164:167], v[96:111]
	v_add_f32_e32 v78, v114, v78
	v_add_f32_e32 v78, v115, v78
	v_add_f32_e32 v78, v116, v78
	v_add_f32_e32 v78, v117, v78
	v_cvt_pk_bf16_f32 v148, v112, v113
	v_cvt_pk_bf16_f32 v149, v114, v115
	ds_read_b64_tr_b16 v[112:113], v214 offset:30720
	ds_read_b64_tr_b16 v[114:115], v214 offset:31232
	v_mfma_f32_32x32x16_bf16 v[80:95], v[70:73], v[164:167], v[80:95]
	v_add_f32_e32 v78, v118, v78
	v_add_f32_e32 v78, v119, v78
	v_add_f32_e32 v78, v120, v78
	v_add_f32_e32 v78, v121, v78
	v_cvt_pk_bf16_f32 v150, v116, v117
	v_cvt_pk_bf16_f32 v151, v118, v119
	ds_read_b64_tr_b16 v[70:71], v214 offset:27648
	ds_read_b64_tr_b16 v[72:73], v214 offset:28160
	v_mfma_f32_32x32x16_bf16 v[96:111], v[74:77], v[156:159], v[96:111]
	v_add_f32_e32 v78, v122, v78
	v_add_f32_e32 v78, v123, v78
	v_add_f32_e32 v78, v124, v78
	v_add_f32_e32 v78, v125, v78
	v_cvt_pk_bf16_f32 v144, v120, v121
	v_cvt_pk_bf16_f32 v145, v122, v123
	ds_read_b64_tr_b16 v[74:75], v214 offset:31744
	ds_read_b64_tr_b16 v[76:77], v214 offset:32256
	v_mfma_f32_32x32x16_bf16 v[80:95], v[66:69], v[156:159], v[80:95]
	v_add_f32_e32 v78, v126, v78
	v_add_f32_e32 v78, v127, v78
	v_add_f32_e32 v78, 0, v78
	v_cvt_pk_bf16_f32 v146, v124, v125
	v_cvt_pk_bf16_f32 v147, v126, v127
	s_add_i32 s1, s25, s69
	s_mov_b32 s24, m0
	s_mov_b32 m0, s1
	s_nop 0
	global_load_lds_dwordx4 v[212:213], off
	s_mov_b32 m0, s24
	s_lshl_b32 s1, s2, 1
	s_add_i32 s24, s1, s72
	s_mov_b32 s27, m0
	s_mov_b32 m0, s24
	s_nop 0
	global_load_lds_dwordx4 v[210:211], off
	s_mov_b32 m0, s27
	s_add_i32 s1, s1, s73
	s_mov_b32 s24, m0
	s_mov_b32 m0, s1
	s_nop 0
	global_load_lds_dwordx4 v[208:209], off
	s_mov_b32 m0, s24
	s_add_i32 s8, s8, 2
	s_waitcnt lgkmcnt(14)
	v_mfma_f32_32x32x16_bf16 v[16:31], v[160:163], v[188:191], v[16:31]
	ds_read_b64_tr_b16 v[66:67], v214 offset:32768
	ds_read_b64_tr_b16 v[68:69], v214 offset:33280
	v_exp_f32_e32 v96, v96
	v_exp_f32_e32 v97, v97
	s_waitcnt lgkmcnt(14)
	v_mfma_f32_32x32x16_bf16 v[48:63], v[160:163], v[128:131], v[48:63]
	ds_read_b64_tr_b16 v[116:117], v214 offset:36864
	ds_read_b64_tr_b16 v[118:119], v214 offset:37376
	v_exp_f32_e32 v98, v98
	v_exp_f32_e32 v99, v99
	v_add_u32_e32 v79, s2, v246
	ds_read_b128 v[204:207], v79
	ds_read_b128 v[200:203], v79 offset:512
	s_waitcnt lgkmcnt(14)
	v_mfma_f32_32x32x16_bf16 v[16:31], v[152:155], v[132:135], v[16:31]
	ds_read_b64_tr_b16 v[120:121], v214 offset:33792
	ds_read_b64_tr_b16 v[122:123], v214 offset:34304
	v_exp_f32_e32 v100, v100
	v_exp_f32_e32 v101, v101
	ds_read_b128 v[196:199], v79 offset:2048
	ds_read_b128 v[192:195], v79 offset:2560
	v_mfma_f32_32x32x16_bf16 v[48:63], v[152:155], v[136:139], v[48:63]
	ds_read_b64_tr_b16 v[124:125], v214 offset:37888
	ds_read_b64_tr_b16 v[126:127], v214 offset:38400
	v_exp_f32_e32 v102, v102
	v_exp_f32_e32 v103, v103
	ds_read_b128 v[188:191], v79 offset:4096
	ds_read_b128 v[184:187], v79 offset:4608
	s_waitcnt lgkmcnt(14)
	v_mfma_f32_32x32x16_bf16 v[16:31], v[148:151], v[140:143], v[16:31]
	ds_read_b64_tr_b16 v[128:129], v214 offset:34816
	ds_read_b64_tr_b16 v[130:131], v214 offset:35328
	v_exp_f32_e32 v104, v104
	v_exp_f32_e32 v105, v105
	ds_read_b128 v[180:183], v79 offset:6144
	ds_read_b128 v[176:179], v79 offset:6656
	v_mfma_f32_32x32x16_bf16 v[48:63], v[148:151], v[112:115], v[48:63]
	ds_read_b64_tr_b16 v[132:133], v214 offset:38912
	ds_read_b64_tr_b16 v[134:135], v214 offset:39424
	v_exp_f32_e32 v106, v106
	v_exp_f32_e32 v107, v107
	v_mfma_f32_32x32x16_bf16 v[16:31], v[144:147], v[70:73], v[16:31]
	ds_read_b64_tr_b16 v[112:113], v214 offset:35840
	ds_read_b64_tr_b16 v[114:115], v214 offset:36352
	v_exp_f32_e32 v108, v108
	v_exp_f32_e32 v109, v109
	v_mfma_f32_32x32x16_bf16 v[48:63], v[144:147], v[74:77], v[48:63]
	ds_read_b64_tr_b16 v[70:71], v214 offset:39936
	ds_read_b64_tr_b16 v[72:73], v214 offset:40448
	v_exp_f32_e32 v110, v110
	v_exp_f32_e32 v111, v111
	s_waitcnt lgkmcnt(14)
	v_mfma_f32_32x32x16_bf16 v[0:15], v[160:163], v[66:69], v[0:15]
	v_exp_f32_e32 v80, v80
	v_exp_f32_e32 v81, v81
	v_mfma_f32_32x32x16_bf16 v[32:47], v[160:163], v[116:119], v[32:47]
	v_exp_f32_e32 v82, v82
	v_exp_f32_e32 v83, v83
	v_mfma_f32_32x32x16_bf16 v[0:15], v[152:155], v[120:123], v[0:15]
	v_exp_f32_e32 v84, v84
	v_exp_f32_e32 v85, v85
	s_waitcnt lgkmcnt(12)
	v_mfma_f32_32x32x16_bf16 v[32:47], v[152:155], v[124:127], v[32:47]
	v_exp_f32_e32 v86, v86
	v_exp_f32_e32 v87, v87
	s_waitcnt lgkmcnt(8)
	v_mfma_f32_32x32x16_bf16 v[0:15], v[148:151], v[128:131], v[0:15]
	v_exp_f32_e32 v88, v88
	v_exp_f32_e32 v89, v89
	s_waitcnt lgkmcnt(4)
	v_mfma_f32_32x32x16_bf16 v[32:47], v[148:151], v[132:135], v[32:47]
	v_exp_f32_e32 v90, v90
	v_exp_f32_e32 v91, v91
	s_waitcnt lgkmcnt(2)
	v_mfma_f32_32x32x16_bf16 v[0:15], v[144:147], v[112:115], v[0:15]
	v_exp_f32_e32 v92, v92
	v_exp_f32_e32 v93, v93
	s_waitcnt lgkmcnt(0)
	v_mfma_f32_32x32x16_bf16 v[32:47], v[144:147], v[70:73], v[32:47]
	v_exp_f32_e32 v94, v94
	v_exp_f32_e32 v95, v95
	s_add_i32 s1, s2, 0x2000
	v_add_f32_e32 v64, v64, v65
	s_cmpk_lg_i32 s2, 0x4000
	v_lshl_add_u64 v[208:209], v[208:209], 0, s[12:13]
	v_lshl_add_u64 v[210:211], v[210:211], 0, s[12:13]
	v_lshl_add_u64 v[212:213], v[212:213], 0, s[12:13]
	s_mov_b32 s27, s25
	s_cselect_b32 s24, s1, 0
	s_cmp_ge_i32 s8, s0
	v_add_f32_e32 v64, v64, v78
	s_waitcnt vmcnt(3) lgkmcnt(0)
	s_barrier
	s_cbranch_scc0 .LBB0_647
	s_add_i32 s0, s8, 1
	s_cmp_ge_i32 s0, s26
	s_mov_b64 s[0:1], -1
	s_cbranch_scc0 .LBB0_650

.LBB0_688:
	v_mbcnt_lo_u32_b32 v212, -1, 0
	v_mbcnt_hi_u32_b32 v212, -1, v212
	v_lshrrev_b32_e32 v213, 5, v212
	v_and_b32_e32 v212, 31, v212
	s_lshr_b32 s52, s75, 1
	s_mov_b32 s54, s66
	s_cmp_eq_u32 s52, 1
	s_cselect_b32 s54, s61, s54
	s_cmp_eq_u32 s52, 2
	s_cselect_b32 s54, s63, s54
	s_cmp_eq_u32 s52, 3
	s_cselect_b32 s54, s67, s54
	s_lshl_b32 s54, s54, 8
	s_lshr_b32 s55, s60, 3
	s_lshl_b32 s55, s55, 13
	s_add_i32 s54, s54, s55
	s_lshr_b32 s55, s85, 1
	s_add_i32 s54, s54, s55
	s_and_b32 s57, s60, 7
	s_bitcmp1_b32 s75, 0
	s_cbranch_scc0 .Lmy_t_q
	s_lshl_b32 s56, s54, 11
	s_lshl_b32 s53, s57, 8
	s_add_u32 s56, s56, s53
	s_add_u32 s56, s56, 0xe800000
	s_add_u32 s58, s22, s56
	s_addc_u32 s59, s23, 0
	v_lshlrev_b32_e32 v254, 11, v212
	v_lshl_or_b32 v254, v213, 7, v254
	global_load_dword v255, v254, s[58:59]
